# remaining two mLSTM scan finish blocks (tile-paired accumulators) rewritten with interleaved reductions and two dwordx4 stores
# speedup vs baseline: 1.0008x; 1.0008x over previous
; template <int N> __device__ __forceinline__ float row16_bcast(float v) { return dppf<0x150 + N>(v); }
; __device__ __forceinline__ float frcp(float x) { return __builtin_amdgcn_rcpf(x); }
; __device__ __forceinline__ bool scan_needfin(int s) { return s >= 0 && s < 35 && !scan_first(s + 1) && s + 1 != 20 && s + 1 != 2; }
;     ...
;     if (s == 21 || s == 3) asm volatile("s_waitcnt vmcnt(0)" ::: "memory");
;     else if (scan_needfin(s - 1)) { if (GDN) asm volatile("s_waitcnt vmcnt(14)" ::: "memory"); else asm volatile("s_waitcnt vmcnt(15)" ::: "memory"); }
;     else { if (GDN) asm volatile("s_waitcnt vmcnt(8)" ::: "memory"); else asm volatile("s_waitcnt vmcnt(9)" ::: "memory"); }
;     __syncthreads();
;     ...
;             S[t] = S[t] * gl + bv; O[t] = o * use.wi + ov; }
;     }
;     if (!GDN) {
; #pragma unroll
;         for (int i = 0; i < 4; ++i) { const float den = row16_bcast<0>(O[NT - 1][i]), fl = row16_bcast<1>(O[NT - 1][i]); const float dv = frcp(fmaxf(fabsf(den), fl));
; #pragma unroll
;             for (int t = 0; t < 4; ++t) O[t][i] *= dv; }
.LBB0_402:
	v_lshlrev_b32_e32 v168, 16, v53
	v_and_b32_e32 v169, 0xffff0000, v53
	v_pk_fma_f32 v[168:169], v[102:103], v[106:107], v[168:169]
	v_lshlrev_b32_e32 v106, 16, v55
	v_and_b32_e32 v107, 0xffff0000, v55
	v_pk_fma_f32 v[170:171], v[102:103], v[110:111], v[106:107]
	v_lshlrev_b32_e32 v106, 16, v33
	v_and_b32_e32 v107, 0xffff0000, v33
	v_pk_fma_f32 v[172:173], v[102:103], v[114:115], v[106:107]
	v_lshlrev_b32_e32 v106, 16, v35
	v_and_b32_e32 v107, 0xffff0000, v35
	v_pk_fma_f32 v[174:175], v[102:103], v[118:119], v[106:107]
	v_max_f32_e32 v106, v193, v193
	v_max_f32_e64 v107, |v187|, |v187|
	v_lshlrev_b32_e32 v166, 16, v52
	v_and_b32_e32 v167, 0xffff0000, v52
	v_max_f32_e32 v106, v107, v106
	v_pk_fma_f32 v[166:167], v[100:101], v[104:105], v[166:167]
	v_lshlrev_b32_e32 v104, 16, v54
	v_and_b32_e32 v105, 0xffff0000, v54
	v_rcp_f32_e32 v106, v106
	v_pk_fma_f32 v[108:109], v[100:101], v[108:109], v[104:105]
	v_lshlrev_b32_e32 v104, 16, v32
	v_and_b32_e32 v105, 0xffff0000, v32
	v_pk_fma_f32 v[110:111], v[100:101], v[112:113], v[104:105]
	v_lshlrev_b32_e32 v104, 16, v34
	v_and_b32_e32 v105, 0xffff0000, v34
	v_pk_fma_f32 v[114:115], v[100:101], v[116:117], v[104:105]
	v_mov_b32_e32 v104, v166
	v_mov_b32_e32 v105, v108
	v_pk_mul_f32 v[104:105], v[104:105], v[106:107] op_sel_hi:[1,0]
	v_max_f32_e32 v107, v186, v186
	v_max_f32_e64 v108, |v179|, |v179|
	v_max_f32_e32 v107, v108, v107
	v_mov_b32_e32 v112, v110
	v_rcp_f32_e32 v110, v107
	v_mov_b32_e32 v113, v114
	v_mov_b32_e32 v108, v167
	v_pk_mul_f32 v[106:107], v[112:113], v[106:107] op_sel_hi:[1,0]
	v_pk_mul_f32 v[112:113], v[108:109], v[110:111] op_sel_hi:[1,0]
	v_max_f32_e32 v108, v178, v178
	v_max_f32_e64 v109, |v165|, |v165|
	v_max_f32_e32 v108, v109, v108
	v_rcp_f32_e32 v116, v108
	v_mov_b32_e32 v114, v111
	v_mov_b32_e32 v108, v168
	v_mov_b32_e32 v109, v170
	v_pk_mul_f32 v[114:115], v[114:115], v[110:111] op_sel_hi:[1,0]
	v_pk_mul_f32 v[108:109], v[108:109], v[116:117] op_sel_hi:[1,0]
	v_max_f32_e32 v111, v164, v164
	v_max_f32_e64 v117, |v163|, |v163|
	v_max_f32_e32 v111, v117, v111
	v_rcp_f32_e32 v164, v111
	s_cmp_gt_u32 s25, 2
	v_mov_b32_e32 v110, v172
	v_mov_b32_e32 v111, v174
	v_mov_b32_e32 v170, v169
	v_mov_b32_e32 v174, v173
	s_cselect_b32 s6, 20, 2
	v_pk_mul_f32 v[110:111], v[110:111], v[116:117] op_sel_hi:[1,0]
	v_pk_mul_f32 v[118:119], v[170:171], v[164:165] op_sel_hi:[1,0]
	v_pk_mul_f32 v[116:117], v[174:175], v[164:165] op_sel_hi:[1,0]
	s_cmp_lt_u32 s4, s6
	s_mov_b64 s[10:11], -1
	s_waitcnt lgkmcnt(0)
	s_barrier
	s_cbranch_scc1 .LBB0_410
; __device__ __forceinline__ float row16_sum(float v) { v += dppf<0xB1>(v); v += dppf<0x4E>(v); v += dppf<0x141>(v); v += dppf<0x140>(v); return v; }
; __device__ __forceinline__ float frsq(float x) { return __builtin_amdgcn_rsqf(x); }
; __device__ __forceinline__ v2u pack4(const f32x4 v) { v2u r; r.x = pk2(v[0], v[1]); r.y = pk2(v[2], v[3]); return r; }
; __device__ __forceinline__ f32x4 unpack4(const v2u w) { f32x4 r; r[0] = bflo(w.x); r[1] = bfhi(w.x); r[2] = bflo(w.y); r[3] = bfhi(w.y); return r; }
; __device__ __forceinline__ const char* upin(const char* p) { asm volatile("" : "+s"(p)); return p; }
; __device__ __forceinline__ char* upin(char* p) { asm volatile("" : "+s"(p)); return p; }
; template <bool GDN> __device__ __forceinline__ void scan_finish(const Frame& F, int b, int h, int dir, const ScanLane& L, int s, float* PEND, const f32x4 (&Oin)[4], const ScanFin& f) {
;     ...
;         f32x4 O[4]; float ss[4] = {0.f, 0.f, 0.f, 0.f};
; #pragma unroll
;         for (int t = 0; t < 4; ++t)
;             { const f32x4 pv = unpack4(f.pend[t]);
; #pragma unroll
;             for (int i = 0; i < 4; ++i) { O[t][i] = Oin[t][i] + pv[i]; ss[i] += O[t][i] * O[t][i]; } }
; #pragma unroll
;         for (int i = 0; i < 4; ++i) ss[i] = frsq(row16_sum(ss[i]) * (1.f / 64.f) + EPS);
;         char* mp = (char*)F.MIX + ((size_t)row0 * 1024 + (GDN ? 0 : 768) + h * 64) * 2;
; #pragma unroll
;         for (int i = 0; i < 4; ++i) { const f32x4 g = unpack4(f.gz[i]); f32x4 ov;
; #pragma unroll
;             for (int t = 0; t < 4; ++t) ov[t] = O[t][i] * ss[i] * g[t];
;             stu<v2u>(upin(mp + i * 2048), L.mix, pack4(ov)); }
	s_lshl_b32 s4, s5, 6
	s_cmp_lt_i32 s5, 4
	s_cselect_b32 s6, s63, s33
	s_add_i32 s6, s6, s4
	s_ashr_i32 s7, s6, 31
	s_lshl_b64 s[6:7], s[6:7], 11
	s_add_u32 s4, s26, s6
	s_addc_u32 s8, s27, s7
	s_add_u32 s6, s4, 0x600
	s_addc_u32 s7, s8, 0
	v_lshlrev_b32_e32 v246, 16, v12
	v_lshlrev_b32_e32 v247, 16, v14
	v_lshlrev_b32_e32 v220, 16, v16
	v_lshlrev_b32_e32 v221, 16, v18
	v_pk_add_f32 v[212:213], v[104:105], v[246:247]
	v_pk_add_f32 v[214:215], v[106:107], v[220:221]
	v_pk_mul_f32 v[204:205], v[212:213], v[212:213]
	v_pk_fma_f32 v[204:205], v[214:215], v[214:215], v[204:205]
	v_and_b32_e32 v246, 0xffff0000, v12
	v_and_b32_e32 v247, 0xffff0000, v14
	v_and_b32_e32 v220, 0xffff0000, v16
	v_and_b32_e32 v221, 0xffff0000, v18
	v_pk_add_f32 v[216:217], v[112:113], v[246:247]
	v_pk_add_f32 v[218:219], v[114:115], v[220:221]
	v_pk_mul_f32 v[206:207], v[216:217], v[216:217]
	v_pk_fma_f32 v[206:207], v[218:219], v[218:219], v[206:207]
	v_lshlrev_b32_e32 v246, 16, v13
	v_lshlrev_b32_e32 v247, 16, v15
	v_lshlrev_b32_e32 v220, 16, v17
	v_lshlrev_b32_e32 v221, 16, v19
	v_pk_add_f32 v[224:225], v[108:109], v[246:247]
	v_pk_add_f32 v[226:227], v[110:111], v[220:221]
	v_pk_mul_f32 v[208:209], v[224:225], v[224:225]
	v_pk_fma_f32 v[208:209], v[226:227], v[226:227], v[208:209]
	v_and_b32_e32 v246, 0xffff0000, v13
	v_and_b32_e32 v247, 0xffff0000, v15
	v_and_b32_e32 v220, 0xffff0000, v17
	v_and_b32_e32 v221, 0xffff0000, v19
	v_pk_add_f32 v[242:243], v[118:119], v[246:247]
	v_pk_add_f32 v[244:245], v[116:117], v[220:221]
	v_pk_mul_f32 v[210:211], v[242:243], v[242:243]
	v_pk_fma_f32 v[210:211], v[244:245], v[244:245], v[210:211]
	v_add_f32_e32 v204, v204, v205
	v_add_f32_e32 v206, v206, v207
	v_add_f32_e32 v208, v208, v209
	v_add_f32_e32 v210, v210, v211
	s_nop 0
	v_add_f32_dpp v204, v204, v204 quad_perm:[1,0,3,2] row_mask:0xf bank_mask:0xf bound_ctrl:1
	v_add_f32_dpp v206, v206, v206 quad_perm:[1,0,3,2] row_mask:0xf bank_mask:0xf bound_ctrl:1
	v_add_f32_dpp v208, v208, v208 quad_perm:[1,0,3,2] row_mask:0xf bank_mask:0xf bound_ctrl:1
	v_add_f32_dpp v210, v210, v210 quad_perm:[1,0,3,2] row_mask:0xf bank_mask:0xf bound_ctrl:1
	v_add_f32_dpp v204, v204, v204 quad_perm:[2,3,0,1] row_mask:0xf bank_mask:0xf bound_ctrl:1
	v_add_f32_dpp v206, v206, v206 quad_perm:[2,3,0,1] row_mask:0xf bank_mask:0xf bound_ctrl:1
	v_add_f32_dpp v208, v208, v208 quad_perm:[2,3,0,1] row_mask:0xf bank_mask:0xf bound_ctrl:1
	v_add_f32_dpp v210, v210, v210 quad_perm:[2,3,0,1] row_mask:0xf bank_mask:0xf bound_ctrl:1
	v_add_f32_dpp v204, v204, v204 row_half_mirror row_mask:0xf bank_mask:0xf bound_ctrl:1
	v_add_f32_dpp v206, v206, v206 row_half_mirror row_mask:0xf bank_mask:0xf bound_ctrl:1
	v_add_f32_dpp v208, v208, v208 row_half_mirror row_mask:0xf bank_mask:0xf bound_ctrl:1
	v_add_f32_dpp v210, v210, v210 row_half_mirror row_mask:0xf bank_mask:0xf bound_ctrl:1
	v_add_f32_dpp v204, v204, v204 row_mirror row_mask:0xf bank_mask:0xf bound_ctrl:1
	v_add_f32_dpp v206, v206, v206 row_mirror row_mask:0xf bank_mask:0xf bound_ctrl:1
	v_add_f32_dpp v208, v208, v208 row_mirror row_mask:0xf bank_mask:0xf bound_ctrl:1
	v_add_f32_dpp v210, v210, v210 row_mirror row_mask:0xf bank_mask:0xf bound_ctrl:1
	v_fmamk_f32 v204, v204, 0x3c800000, v231
	v_fmamk_f32 v206, v206, 0x3c800000, v231
	v_fmamk_f32 v208, v208, 0x3c800000, v231
	v_fmamk_f32 v210, v210, 0x3c800000, v231
	v_rsq_f32_e32 v204, v204
	v_rsq_f32_e32 v206, v206
	v_rsq_f32_e32 v208, v208
	v_rsq_f32_e32 v210, v210
	v_lshlrev_b32_e32 v246, 16, v130
	v_and_b32_e32 v247, 0xffff0000, v130
	v_lshlrev_b32_e32 v220, 16, v131
	v_and_b32_e32 v221, 0xffff0000, v131
	v_pk_mul_f32 v[212:213], v[212:213], v[204:205] op_sel_hi:[1,0]
	v_pk_mul_f32 v[214:215], v[214:215], v[204:205] op_sel_hi:[1,0]
	v_pk_mul_f32 v[212:213], v[212:213], v[246:247]
	v_pk_mul_f32 v[214:215], v[214:215], v[220:221]
	v_lshlrev_b32_e32 v246, 16, v132
	v_and_b32_e32 v247, 0xffff0000, v132
	v_lshlrev_b32_e32 v220, 16, v133
	v_and_b32_e32 v221, 0xffff0000, v133
	v_pk_mul_f32 v[216:217], v[216:217], v[206:207] op_sel_hi:[1,0]
	v_pk_mul_f32 v[218:219], v[218:219], v[206:207] op_sel_hi:[1,0]
	v_pk_mul_f32 v[216:217], v[216:217], v[246:247]
	v_pk_mul_f32 v[218:219], v[218:219], v[220:221]
	v_lshlrev_b32_e32 v246, 16, v134
	v_and_b32_e32 v247, 0xffff0000, v134
	v_lshlrev_b32_e32 v220, 16, v135
	v_and_b32_e32 v221, 0xffff0000, v135
	v_pk_mul_f32 v[224:225], v[224:225], v[208:209] op_sel_hi:[1,0]
	v_pk_mul_f32 v[226:227], v[226:227], v[208:209] op_sel_hi:[1,0]
	v_pk_mul_f32 v[224:225], v[224:225], v[246:247]
	v_pk_mul_f32 v[226:227], v[226:227], v[220:221]
	v_lshlrev_b32_e32 v246, 16, v136
	v_and_b32_e32 v247, 0xffff0000, v136
	v_lshlrev_b32_e32 v220, 16, v137
	v_and_b32_e32 v221, 0xffff0000, v137
	v_pk_mul_f32 v[242:243], v[242:243], v[210:211] op_sel_hi:[1,0]
	v_pk_mul_f32 v[244:245], v[244:245], v[210:211] op_sel_hi:[1,0]
	v_pk_mul_f32 v[242:243], v[242:243], v[246:247]
	v_pk_mul_f32 v[244:245], v[244:245], v[220:221]
	v_cvt_pk_bf16_f32 v204, v212, v213
	v_cvt_pk_bf16_f32 v205, v214, v215
	v_cvt_pk_bf16_f32 v210, v216, v217
	v_cvt_pk_bf16_f32 v211, v218, v219
	v_cvt_pk_bf16_f32 v206, v224, v225
	v_cvt_pk_bf16_f32 v207, v226, v227
	v_cvt_pk_bf16_f32 v218, v242, v243
	v_cvt_pk_bf16_f32 v219, v244, v245
	v_and_b32_e32 v220, 1, v232
	v_mul_u32_u24_e32 v220, 0x7f8, v220
	v_add_u32_e32 v220, v162, v220
	s_mov_b32 vcc_lo, 0x55555555
	s_mov_b32 vcc_hi, 0x55555555
	v_cndmask_b32_dpp v208, v210, v204, vcc quad_perm:[1,0,3,2] row_mask:0xf bank_mask:0xf
	v_cndmask_b32_dpp v209, v211, v205, vcc quad_perm:[1,0,3,2] row_mask:0xf bank_mask:0xf
	v_cndmask_b32_dpp v216, v218, v206, vcc quad_perm:[1,0,3,2] row_mask:0xf bank_mask:0xf
	v_cndmask_b32_dpp v217, v219, v207, vcc quad_perm:[1,0,3,2] row_mask:0xf bank_mask:0xf
	s_not_b64 vcc, vcc
	v_cndmask_b32_dpp v210, v204, v210, vcc quad_perm:[1,0,3,2] row_mask:0xf bank_mask:0xf
	v_cndmask_b32_dpp v211, v205, v211, vcc quad_perm:[1,0,3,2] row_mask:0xf bank_mask:0xf
	v_cndmask_b32_dpp v218, v206, v218, vcc quad_perm:[1,0,3,2] row_mask:0xf bank_mask:0xf
	v_cndmask_b32_dpp v219, v207, v219, vcc quad_perm:[1,0,3,2] row_mask:0xf bank_mask:0xf
	global_store_dwordx4 v220, v[208:211], s[6:7]
	s_add_u32 s6, s4, 0xe00
	s_addc_u32 s7, s8, 0
	s_add_u32 s6, s4, 0x1600
	s_addc_u32 s7, s8, 0
	global_store_dwordx4 v220, v[216:219], s[6:7]
	s_add_u32 s6, s4, 0x1e00
	s_addc_u32 s7, s8, 0
	s_cbranch_execz .LBB0_411

; template <int N> __device__ __forceinline__ float row16_bcast(float v) { return dppf<0x150 + N>(v); }
; __device__ __forceinline__ float frcp(float x) { return __builtin_amdgcn_rcpf(x); }
;     ...
;             S[t] = S[t] * gl + bv; O[t] = o * use.wi + ov; }
;     }
;     if (!GDN) {
; #pragma unroll
;         for (int i = 0; i < 4; ++i) { const float den = row16_bcast<0>(O[NT - 1][i]), fl = row16_bcast<1>(O[NT - 1][i]); const float dv = frcp(fmaxf(fabsf(den), fl));
; #pragma unroll
;             for (int t = 0; t < 4; ++t) O[t][i] *= dv; }
.LBB0_441:
	v_lshlrev_b32_e32 v168, 16, v97
	v_and_b32_e32 v169, 0xffff0000, v97
	v_pk_fma_f32 v[168:169], v[62:63], v[106:107], v[168:169]
	v_lshlrev_b32_e32 v106, 16, v98
	v_and_b32_e32 v107, 0xffff0000, v98
	v_lshlrev_b32_e32 v166, 16, v96
	v_and_b32_e32 v167, 0xffff0000, v96
	v_pk_fma_f32 v[106:107], v[60:61], v[108:109], v[106:107]
	v_lshlrev_b32_e32 v108, 16, v68
	v_and_b32_e32 v109, 0xffff0000, v68
	v_pk_fma_f32 v[104:105], v[60:61], v[104:105], v[166:167]
	v_lshlrev_b32_e32 v166, 16, v99
	v_and_b32_e32 v167, 0xffff0000, v99
	v_pk_fma_f32 v[108:109], v[60:61], v[112:113], v[108:109]
	v_lshlrev_b32_e32 v112, 16, v70
	v_and_b32_e32 v113, 0xffff0000, v70
	v_pk_fma_f32 v[110:111], v[62:63], v[110:111], v[166:167]
	v_lshlrev_b32_e32 v166, 16, v69
	v_and_b32_e32 v167, 0xffff0000, v69
	v_pk_fma_f32 v[116:117], v[60:61], v[116:117], v[112:113]
	v_mov_b32_e32 v112, v104
	v_mov_b32_e32 v113, v106
	v_max_f32_e32 v104, v161, v161
	v_max_f32_e64 v106, |v160|, |v160|
	v_pk_fma_f32 v[166:167], v[62:63], v[114:115], v[166:167]
	v_lshlrev_b32_e32 v114, 16, v71
	v_and_b32_e32 v115, 0xffff0000, v71
	v_max_f32_e32 v104, v106, v104
	v_pk_fma_f32 v[170:171], v[62:63], v[118:119], v[114:115]
	v_max_f32_e32 v114, v185, v185
	v_max_f32_e64 v115, |v184|, |v184|
	v_mov_b32_e32 v118, v108
	v_rcp_f32_e32 v108, v104
	v_max_f32_e32 v114, v115, v114
	v_rcp_f32_e32 v114, v114
	v_mov_b32_e32 v106, v105
	v_pk_mul_f32 v[104:105], v[106:107], v[108:109] op_sel_hi:[1,0]
	v_max_f32_e32 v106, v159, v159
	v_max_f32_e64 v107, |v158|, |v158|
	v_mov_b32_e32 v119, v116
	v_max_f32_e32 v106, v107, v106
	v_pk_mul_f32 v[112:113], v[112:113], v[114:115] op_sel_hi:[1,0]
	v_pk_mul_f32 v[114:115], v[118:119], v[114:115] op_sel_hi:[1,0]
	v_rcp_f32_e32 v118, v106
	v_mov_b32_e32 v116, v109
	v_pk_mul_f32 v[106:107], v[116:117], v[108:109] op_sel_hi:[1,0]
	v_mov_b32_e32 v108, v168
	v_mov_b32_e32 v109, v110
	v_pk_mul_f32 v[116:117], v[108:109], v[118:119] op_sel_hi:[1,0]
	v_max_f32_e32 v109, v157, v157
	v_max_f32_e64 v110, |v156|, |v156|
	v_max_f32_e32 v109, v110, v109
	v_rcp_f32_e32 v156, v109
	v_mov_b32_e32 v108, v166
	v_mov_b32_e32 v109, v170
	v_mov_b32_e32 v110, v169
	v_mov_b32_e32 v170, v167
	v_pk_mul_f32 v[118:119], v[108:109], v[118:119] op_sel_hi:[1,0]
	v_pk_mul_f32 v[110:111], v[110:111], v[156:157] op_sel_hi:[1,0]
	v_pk_mul_f32 v[108:109], v[170:171], v[156:157] op_sel_hi:[1,0]
	s_cmp_lt_u32 s0, 16
	s_mov_b64 s[10:11], -1
	s_waitcnt lgkmcnt(0)
	s_barrier
	s_cbranch_scc1 .LBB0_453
; __device__ __forceinline__ float row16_sum(float v) { v += dppf<0xB1>(v); v += dppf<0x4E>(v); v += dppf<0x141>(v); v += dppf<0x140>(v); return v; }
; __device__ __forceinline__ float frsq(float x) { return __builtin_amdgcn_rsqf(x); }
; __device__ __forceinline__ v2u pack4(const f32x4 v) { v2u r; r.x = pk2(v[0], v[1]); r.y = pk2(v[2], v[3]); return r; }
; __device__ __forceinline__ f32x4 unpack4(const v2u w) { f32x4 r; r[0] = bflo(w.x); r[1] = bfhi(w.x); r[2] = bflo(w.y); r[3] = bfhi(w.y); return r; }
; __device__ __forceinline__ const char* upin(const char* p) { asm volatile("" : "+s"(p)); return p; }
; __device__ __forceinline__ char* upin(char* p) { asm volatile("" : "+s"(p)); return p; }
; template <bool GDN> __device__ __forceinline__ void scan_finish(const Frame& F, int b, int h, int dir, const ScanLane& L, int s, float* PEND, const f32x4 (&Oin)[4], const ScanFin& f) {
;     ...
;         f32x4 O[4]; float ss[4] = {0.f, 0.f, 0.f, 0.f};
; #pragma unroll
;         for (int t = 0; t < 4; ++t)
;             { const f32x4 pv = unpack4(f.pend[t]);
; #pragma unroll
;             for (int i = 0; i < 4; ++i) { O[t][i] = Oin[t][i] + pv[i]; ss[i] += O[t][i] * O[t][i]; } }
; #pragma unroll
;         for (int i = 0; i < 4; ++i) ss[i] = frsq(row16_sum(ss[i]) * (1.f / 64.f) + EPS);
;         char* mp = (char*)F.MIX + ((size_t)row0 * 1024 + (GDN ? 0 : 768) + h * 64) * 2;
; #pragma unroll
;         for (int i = 0; i < 4; ++i) { const f32x4 g = unpack4(f.gz[i]); f32x4 ov;
; #pragma unroll
;             for (int t = 0; t < 4; ++t) ov[t] = O[t][i] * ss[i] * g[t];
;             stu<v2u>(upin(mp + i * 2048), L.mix, pack4(ov)); }
	s_lshl_b32 s0, s1, 6
	s_cmp_lt_i32 s1, 4
	s_cselect_b32 s4, s63, s33
	s_add_i32 s4, s4, s0
	s_ashr_i32 s5, s4, 31
	s_lshl_b64 s[4:5], s[4:5], 11
	s_add_u32 s0, s26, s4
	s_addc_u32 s6, s27, s5
	s_add_u32 s4, s0, 0x600
	s_addc_u32 s5, s6, 0
	v_lshlrev_b32_e32 v246, 16, v12
	v_lshlrev_b32_e32 v247, 16, v14
	v_lshlrev_b32_e32 v220, 16, v16
	v_lshlrev_b32_e32 v221, 16, v18
	v_pk_add_f32 v[212:213], v[112:113], v[246:247]
	v_pk_add_f32 v[214:215], v[114:115], v[220:221]
	v_pk_mul_f32 v[204:205], v[212:213], v[212:213]
	v_pk_fma_f32 v[204:205], v[214:215], v[214:215], v[204:205]
	v_and_b32_e32 v246, 0xffff0000, v12
	v_and_b32_e32 v247, 0xffff0000, v14
	v_and_b32_e32 v220, 0xffff0000, v16
	v_and_b32_e32 v221, 0xffff0000, v18
	v_pk_add_f32 v[216:217], v[104:105], v[246:247]
	v_pk_add_f32 v[218:219], v[106:107], v[220:221]
	v_pk_mul_f32 v[206:207], v[216:217], v[216:217]
	v_pk_fma_f32 v[206:207], v[218:219], v[218:219], v[206:207]
	v_lshlrev_b32_e32 v246, 16, v13
	v_lshlrev_b32_e32 v247, 16, v15
	v_lshlrev_b32_e32 v220, 16, v17
	v_lshlrev_b32_e32 v221, 16, v19
	v_pk_add_f32 v[224:225], v[116:117], v[246:247]
	v_pk_add_f32 v[226:227], v[118:119], v[220:221]
	v_pk_mul_f32 v[208:209], v[224:225], v[224:225]
	v_pk_fma_f32 v[208:209], v[226:227], v[226:227], v[208:209]
	v_and_b32_e32 v246, 0xffff0000, v13
	v_and_b32_e32 v247, 0xffff0000, v15
	v_and_b32_e32 v220, 0xffff0000, v17
	v_and_b32_e32 v221, 0xffff0000, v19
	v_pk_add_f32 v[242:243], v[110:111], v[246:247]
	v_pk_add_f32 v[244:245], v[108:109], v[220:221]
	v_pk_mul_f32 v[210:211], v[242:243], v[242:243]
	v_pk_fma_f32 v[210:211], v[244:245], v[244:245], v[210:211]
	v_add_f32_e32 v204, v204, v205
	v_add_f32_e32 v206, v206, v207
	v_add_f32_e32 v208, v208, v209
	v_add_f32_e32 v210, v210, v211
	s_nop 0
	v_add_f32_dpp v204, v204, v204 quad_perm:[1,0,3,2] row_mask:0xf bank_mask:0xf bound_ctrl:1
	v_add_f32_dpp v206, v206, v206 quad_perm:[1,0,3,2] row_mask:0xf bank_mask:0xf bound_ctrl:1
	v_add_f32_dpp v208, v208, v208 quad_perm:[1,0,3,2] row_mask:0xf bank_mask:0xf bound_ctrl:1
	v_add_f32_dpp v210, v210, v210 quad_perm:[1,0,3,2] row_mask:0xf bank_mask:0xf bound_ctrl:1
	v_add_f32_dpp v204, v204, v204 quad_perm:[2,3,0,1] row_mask:0xf bank_mask:0xf bound_ctrl:1
	v_add_f32_dpp v206, v206, v206 quad_perm:[2,3,0,1] row_mask:0xf bank_mask:0xf bound_ctrl:1
	v_add_f32_dpp v208, v208, v208 quad_perm:[2,3,0,1] row_mask:0xf bank_mask:0xf bound_ctrl:1
	v_add_f32_dpp v210, v210, v210 quad_perm:[2,3,0,1] row_mask:0xf bank_mask:0xf bound_ctrl:1
	v_add_f32_dpp v204, v204, v204 row_half_mirror row_mask:0xf bank_mask:0xf bound_ctrl:1
	v_add_f32_dpp v206, v206, v206 row_half_mirror row_mask:0xf bank_mask:0xf bound_ctrl:1
	v_add_f32_dpp v208, v208, v208 row_half_mirror row_mask:0xf bank_mask:0xf bound_ctrl:1
	v_add_f32_dpp v210, v210, v210 row_half_mirror row_mask:0xf bank_mask:0xf bound_ctrl:1
	v_add_f32_dpp v204, v204, v204 row_mirror row_mask:0xf bank_mask:0xf bound_ctrl:1
	v_add_f32_dpp v206, v206, v206 row_mirror row_mask:0xf bank_mask:0xf bound_ctrl:1
	v_add_f32_dpp v208, v208, v208 row_mirror row_mask:0xf bank_mask:0xf bound_ctrl:1
	v_add_f32_dpp v210, v210, v210 row_mirror row_mask:0xf bank_mask:0xf bound_ctrl:1
	v_fmamk_f32 v204, v204, 0x3c800000, v231
	v_fmamk_f32 v206, v206, 0x3c800000, v231
	v_fmamk_f32 v208, v208, 0x3c800000, v231
	v_fmamk_f32 v210, v210, 0x3c800000, v231
	v_rsq_f32_e32 v204, v204
	v_rsq_f32_e32 v206, v206
	v_rsq_f32_e32 v208, v208
	v_rsq_f32_e32 v210, v210
	v_lshlrev_b32_e32 v246, 16, v130
	v_and_b32_e32 v247, 0xffff0000, v130
	v_lshlrev_b32_e32 v220, 16, v131
	v_and_b32_e32 v221, 0xffff0000, v131
	v_pk_mul_f32 v[212:213], v[212:213], v[204:205] op_sel_hi:[1,0]
	v_pk_mul_f32 v[214:215], v[214:215], v[204:205] op_sel_hi:[1,0]
	v_pk_mul_f32 v[212:213], v[212:213], v[246:247]
	v_pk_mul_f32 v[214:215], v[214:215], v[220:221]
	v_lshlrev_b32_e32 v246, 16, v132
	v_and_b32_e32 v247, 0xffff0000, v132
	v_lshlrev_b32_e32 v220, 16, v133
	v_and_b32_e32 v221, 0xffff0000, v133
	v_pk_mul_f32 v[216:217], v[216:217], v[206:207] op_sel_hi:[1,0]
	v_pk_mul_f32 v[218:219], v[218:219], v[206:207] op_sel_hi:[1,0]
	v_pk_mul_f32 v[216:217], v[216:217], v[246:247]
	v_pk_mul_f32 v[218:219], v[218:219], v[220:221]
	v_lshlrev_b32_e32 v246, 16, v134
	v_and_b32_e32 v247, 0xffff0000, v134
	v_lshlrev_b32_e32 v220, 16, v135
	v_and_b32_e32 v221, 0xffff0000, v135
	v_pk_mul_f32 v[224:225], v[224:225], v[208:209] op_sel_hi:[1,0]
	v_pk_mul_f32 v[226:227], v[226:227], v[208:209] op_sel_hi:[1,0]
	v_pk_mul_f32 v[224:225], v[224:225], v[246:247]
	v_pk_mul_f32 v[226:227], v[226:227], v[220:221]
	v_lshlrev_b32_e32 v246, 16, v136
	v_and_b32_e32 v247, 0xffff0000, v136
	v_lshlrev_b32_e32 v220, 16, v137
	v_and_b32_e32 v221, 0xffff0000, v137
	v_pk_mul_f32 v[242:243], v[242:243], v[210:211] op_sel_hi:[1,0]
	v_pk_mul_f32 v[244:245], v[244:245], v[210:211] op_sel_hi:[1,0]
	v_pk_mul_f32 v[242:243], v[242:243], v[246:247]
	v_pk_mul_f32 v[244:245], v[244:245], v[220:221]
	v_cvt_pk_bf16_f32 v204, v212, v213
	v_cvt_pk_bf16_f32 v205, v214, v215
	v_cvt_pk_bf16_f32 v210, v216, v217
	v_cvt_pk_bf16_f32 v211, v218, v219
	v_cvt_pk_bf16_f32 v206, v224, v225
	v_cvt_pk_bf16_f32 v207, v226, v227
	v_cvt_pk_bf16_f32 v218, v242, v243
	v_cvt_pk_bf16_f32 v219, v244, v245
	v_and_b32_e32 v220, 1, v232
	v_mul_u32_u24_e32 v220, 0x7f8, v220
	v_add_u32_e32 v220, v153, v220
	s_mov_b32 vcc_lo, 0x55555555
	s_mov_b32 vcc_hi, 0x55555555
	v_cndmask_b32_dpp v208, v210, v204, vcc quad_perm:[1,0,3,2] row_mask:0xf bank_mask:0xf
	v_cndmask_b32_dpp v209, v211, v205, vcc quad_perm:[1,0,3,2] row_mask:0xf bank_mask:0xf
	v_cndmask_b32_dpp v216, v218, v206, vcc quad_perm:[1,0,3,2] row_mask:0xf bank_mask:0xf
	v_cndmask_b32_dpp v217, v219, v207, vcc quad_perm:[1,0,3,2] row_mask:0xf bank_mask:0xf
	s_not_b64 vcc, vcc
	v_cndmask_b32_dpp v210, v204, v210, vcc quad_perm:[1,0,3,2] row_mask:0xf bank_mask:0xf
	v_cndmask_b32_dpp v211, v205, v211, vcc quad_perm:[1,0,3,2] row_mask:0xf bank_mask:0xf
	v_cndmask_b32_dpp v218, v206, v218, vcc quad_perm:[1,0,3,2] row_mask:0xf bank_mask:0xf
	v_cndmask_b32_dpp v219, v207, v219, vcc quad_perm:[1,0,3,2] row_mask:0xf bank_mask:0xf
	global_store_dwordx4 v220, v[208:211], s[4:5]
	s_add_u32 s4, s0, 0xe00
	s_addc_u32 s5, s6, 0
	s_add_u32 s4, s0, 0x1600
	s_addc_u32 s5, s6, 0
	global_store_dwordx4 v220, v[216:219], s[4:5]
	s_add_u32 s4, s0, 0x1e00
	s_addc_u32 s5, s6, 0
	s_cbranch_execz .LBB0_454
